# P0 weight-conversion items processed in reverse order (w_in converted last so its bf16 image is the most recent thing in the last-level cache when P1 starts)
# speedup vs baseline: 1.0001x; 1.0001x over previous
.LBB0_15:
	v_writelane_b32 v254, s6, 62
	s_xor_b64 s[0:1], s[6:7], -1
	s_mul_i32 s3, s44, 9
	v_writelane_b32 v255, s0, 0
	s_cmp_le_i32 s28, s3
	v_writelane_b32 v254, s7, 63
	v_writelane_b32 v255, s1, 1
	s_cselect_b64 s[0:1], -1, 0
	s_cmp_lt_i32 s3, s29
	s_cselect_b64 s[6:7], -1, 0
	s_and_b64 s[0:1], s[0:1], s[6:7]
	v_writelane_b32 v255, s3, 2
	s_add_i32 s34, s3, 1
	s_mov_b32 s45, s77
	s_cmp_lt_i32 s34, s29
	v_writelane_b32 v255, s44, 3
	s_cselect_b64 s[6:7], -1, 0
	s_andn2_b64 vcc, exec, s[0:1]
	v_writelane_b32 v255, s45, 4
	s_cbranch_vccnz .LBB0_117
	s_waitcnt vmcnt(1)
	v_mov_b32_e32 v46, v0
	s_mov_b64 s[44:45], s[72:73]
	s_load_dwordx2 s[16:17], s[44:45], 0x98
	s_load_dwordx4 s[40:43], s[44:45], 0x8
	v_readfirstlane_b32 s0, v46
	s_ashr_i32 s1, s0, 6
	v_readlane_b32 s0, v253, 8
	s_add_i32 s22, s0, s1
	s_cmp_gt_i32 s22, 0x17dff
	v_and_b32_e32 v1, 63, v46
	s_cbranch_scc1 .LBB0_52
	v_readlane_b32 s14, v255, 3
	v_readlane_b32 s15, v255, 4
	s_mul_i32 s0, s14, 0xac00000
	s_lshl_b64 s[12:13], s[14:15], 26
	s_mul_i32 s3, s14, 0xb440000
	s_load_dwordx2 s[14:15], s[44:45], 0x68
	s_load_dwordx4 s[48:51], s[44:45], 0x78
	s_load_dwordx2 s[18:19], s[44:45], 0x88
	s_waitcnt lgkmcnt(0)
	s_add_u32 s38, s42, s3
	s_addc_u32 s39, s43, 0
	s_add_u32 s42, s14, s12
	s_addc_u32 s43, s15, s13
	v_and_b32_e32 v4, 7, v46
	s_add_u32 s46, s18, s0
	v_lshlrev_b32_e32 v2, 4, v4
	s_addc_u32 s47, s19, 0
	s_lshl_b32 s1, s1, 14
	v_lshlrev_b32_e32 v47, 2, v4
	s_waitcnt vmcnt(0)
	v_mul_u32_u24_e32 v8, 0x420, v4
	v_lshl_add_u64 v[4:5], s[16:17], 0, v[2:3]
	s_mov_b64 s[12:13], 0x12a00000
	s_add_i32 s1, s1, 0
	v_lshrrev_b32_e32 v48, 3, v1
	v_lshl_add_u64 v[36:37], v[4:5], 0, s[12:13]
	s_mov_b64 s[12:13], 0x7e00000
	v_add_u32_e32 v6, s1, v2
	v_mul_u32_u24_e32 v7, 0x84, v48
	v_lshl_add_u64 v[38:39], v[4:5], 0, s[12:13]
	s_mov_b64 s[12:13], 0x5e00000
	v_lshlrev_b32_e32 v2, 2, v48
	v_lshl_add_u64 v[40:41], v[4:5], 0, s[12:13]
	s_mov_b64 s[12:13], 0x200000
	v_add_u32_e32 v53, v6, v7
	v_or_b32_e32 v49, 8, v48
	v_or_b32_e32 v50, 16, v48
	v_or_b32_e32 v51, 24, v48
	v_add3_u32 v52, s1, v8, v2
	v_lshl_add_u64 v[42:43], v[4:5], 0, s[12:13]
	s_sub_i32 s1, 0x17dff, s22
	s_lshl_b32 s1, s1, 5
	s_lshl_b32 s3, s64, 5
	s_sub_i32 s3, 0, s3
	v_add_u32_e32 v54, 0x420, v53
	v_add_u32_e32 v55, 0x428, v53
	v_add_u32_e32 v56, 0x840, v53
	v_add_u32_e32 v57, 0x848, v53
	v_add_u32_e32 v58, 0xc60, v53
	v_add_u32_e32 v59, 0xc68, v53
	v_add_u32_e32 v60, 0x1080, v53
	v_add_u32_e32 v61, 0x1088, v53
	v_add_u32_e32 v62, 0x14a0, v53
	v_add_u32_e32 v63, 0x14a8, v53
	v_add_u32_e32 v64, 0x18c0, v53
	v_add_u32_e32 v65, 0x18c8, v53
	v_add_u32_e32 v66, 0x1ce0, v53
	v_add_u32_e32 v67, 0x1ce8, v53
	s_sub_i32 s18, 0x17dff, s22
	s_branch .LBB0_20

.LBB0_19:
	s_sub_i32 s18, s18, s64
	s_add_i32 s1, s1, s3
	s_cmp_gt_i32 s18, -1
	s_cbranch_scc0 .LBB0_52
